# scan consumer passes the chunk barrier one step early (after its last stage read), prefetches the next chunk's first two steps in the tail; y flush delayed one chunk with a ring of 3 ybufs
# speedup vs baseline: 1.0879x; 1.0088x over previous
; #define LAS __attribute__((address_space(3)))
; DI void rwkv_scan_phase(int wv, const Params& P, LAS unsigned char* lds) {
;     ...
;             const int cg = lane & 15, rloc = wave * 4 + (lane >> 4);
;             f32x4 S = (f32x4){0.f, 0.f, 0.f, 0.f};
;             __syncthreads();
;             __builtin_amdgcn_s_setprio(3);
; #pragma unroll 1
;             for (int ck = 0; ck < nck; ++ck) { const int buf = ck & 1;
;                 const LAS float* sb = stg + buf * RW_T * 5 * 64 + 4 * cg; const LAS float* vb = vst + buf * RW_T * 8 + rloc; LAS float* yb = ybuf + buf * RW_T * 128 + wave * 64 + lane;
;                 const unsigned sba = (unsigned)(size_t)sb, vba = (unsigned)(size_t)vb;
;                 f32x4 nkA, ddA, bbA, kpA, rrA, nkB, ddB, bbB, kpB, rrB; float vvA, vvB;
;     ...
;                 f32x2 yacc = (f32x2){0.f, 0.f};
;                 unsigned sbt = sba, vbt = vba; LAS float* ybt = yb;
;                 RW_LDS_LOAD(A, 0); RW_LDS_WAIT(A);
; #pragma unroll 1
;                 for (int tt = 0; tt < RW_T; tt += 16) { sbt = sba + (unsigned)tt * 1280u; vbt = vba + (unsigned)tt * 32u; ybt = yb + tt * 128;
;                     RW_LDS_LOAD(B, 1); RW_STEP(A, 0); RW_LDS_WAIT(B);
;                     RW_LDS_LOAD(A, 2); RW_STEP(B, 1); RW_LDS_WAIT(A);
;                     RW_LDS_LOAD(B, 3); RW_STEP(A, 2); RW_LDS_WAIT(B);
;                     RW_LDS_LOAD(A, 4); RW_STEP(B, 3); RW_LDS_WAIT(A);
;                     RW_LDS_LOAD(B, 5); RW_STEP(A, 4); RW_LDS_WAIT(B);
;                     RW_LDS_LOAD(A, 6); RW_STEP(B, 5); RW_LDS_WAIT(A);
;                     RW_LDS_LOAD(B, 7); RW_STEP(A, 6); RW_LDS_WAIT(B);
;                     RW_LDS_LOAD(A, 8); RW_STEP(B, 7); RW_LDS_WAIT(A);
;                     RW_LDS_LOAD(B, 9); RW_STEP(A, 8); RW_LDS_WAIT(B);
;                     RW_LDS_LOAD(A, 10); RW_STEP(B, 9); RW_LDS_WAIT(A);
;                     RW_LDS_LOAD(B, 11); RW_STEP(A, 10); RW_LDS_WAIT(B);
;                     RW_LDS_LOAD(A, 12); RW_STEP(B, 11); RW_LDS_WAIT(A);
;                     RW_LDS_LOAD(B, 13); RW_STEP(A, 12); RW_LDS_WAIT(B);
;                     RW_LDS_LOAD(A, 14); RW_STEP(B, 13); RW_LDS_WAIT(A);
;                     RW_LDS_LOAD(B, 15); RW_STEP(A, 14); RW_LDS_WAIT(B);
;                     RW_LDS_LOAD(A, 16); RW_STEP(B, 15); RW_LDS_WAIT(A);
;                 }
.LBB0_3177:
	s_waitcnt lgkmcnt(0)
	s_barrier
	s_and_saveexec_b64 s[20:21], s[2:3]
	s_xor_b64 s[20:21], exec, s[20:21]
	s_cbranch_execz .LBB0_3185
	s_barrier
	s_setprio 3
	v_mov_b32_e32 v73, 0
	v_mov_b32_e32 v58, 0
	v_mov_b32_e32 v59, 0
	v_mov_b32_e32 v60, 0
	v_mov_b32_e32 v61, 0
	s_mov_b32 s47, 0
	s_mov_b32 s42, 0
	s_lshl_b32 s40, s47, 5
	s_and_b32 s40, s40, 32
	s_mul_i32 s41, s40, 0x500
	v_add_u32_e32 v74, s41, v45
	v_add_u32_e32 v73, v74, v45
	v_lshl_add_u32 v75, s40, 5, v63
	v_add_u32_e32 v72, s42, v66
	s_lshl_b32 s41, s40, 3
	s_add_i32 s41, s41, 0x20800
	v_add_u32_e32 v40, s41, v45
	ds_read_b128 v[0:3], v73
	ds_read_b128 v[16:19], v73 offset:16
	ds_read_b32 v42, v75
	ds_read_b128 v[4:7], v74 offset:512
	ds_read_b128 v[8:11], v74 offset:768
	ds_read_b128 v[12:15], v74 offset:1024
	ds_read_b128 v[20:23], v73 offset:1280
	ds_read_b128 v[36:39], v73 offset:1296
	ds_read_b32 v62, v75 offset:32
	ds_read_b128 v[24:27], v74 offset:1792
	ds_read_b128 v[28:31], v74 offset:2048
	ds_read_b128 v[32:35], v74 offset:2304
.Lscan_chunk:
	s_waitcnt lgkmcnt(6)
	v_pk_mul_f32 v[0:1], v[58:59], v[0:1] op_sel_hi:[0,1]
	ds_read_b128 v[46:49], v73 offset:2560
	v_pk_fma_f32 v[0:1], v[58:59], v[2:3], v[0:1] op_sel:[1,0,0] op_sel_hi:[1,1,1]
	ds_read_b128 v[76:79], v73 offset:2576
	v_pk_fma_f32 v[0:1], v[60:61], v[16:17], v[0:1] op_sel_hi:[0,1,1]
	ds_read_b32 v44, v75 offset:64
	v_pk_fma_f32 v[0:1], v[60:61], v[18:19], v[0:1] op_sel:[1,0,0] op_sel_hi:[1,1,1]
	v_pk_mul_f32 v[12:13], v[12:13], v[42:43] op_sel_hi:[1,0]
	v_pk_mul_f32 v[14:15], v[14:15], v[42:43] op_sel_hi:[1,0]
	v_add_f32_dpp v0, v0, v0 quad_perm:[1,0,3,2] row_mask:0xf bank_mask:0xf bound_ctrl:1
	v_pk_fma_f32 v[12:13], v[58:59], v[4:5], v[12:13]
	v_pk_fma_f32 v[14:15], v[60:61], v[6:7], v[14:15]
	v_add_f32_dpp v0, v0, v0 quad_perm:[2,3,0,1] row_mask:0xf bank_mask:0xf bound_ctrl:1
	ds_read_b128 v[50:53], v74 offset:3072
	ds_read_b128 v[54:57], v74 offset:3328
	v_add_f32_dpp v0, v0, v0 row_half_mirror row_mask:0xf bank_mask:0xf bound_ctrl:1
	ds_read_b128 v[68:71], v74 offset:3584
	s_nop 0
	v_add_f32_dpp v0, v0, v0 row_mirror row_mask:0xf bank_mask:0xf bound_ctrl:1
	v_pk_fma_f32 v[58:59], v[8:9], v[0:1], v[12:13] op_sel_hi:[1,0,1]
	v_pk_fma_f32 v[60:61], v[10:11], v[0:1], v[14:15] op_sel_hi:[1,0,1]
	s_waitcnt lgkmcnt(6)
	v_pk_mul_f32 v[20:21], v[58:59], v[20:21] op_sel_hi:[0,1]
	ds_read_b128 v[0:3], v73 offset:3840
	v_pk_fma_f32 v[20:21], v[58:59], v[22:23], v[20:21] op_sel:[1,0,0] op_sel_hi:[1,1,1]
	ds_read_b128 v[16:19], v73 offset:3856
	v_pk_fma_f32 v[20:21], v[60:61], v[36:37], v[20:21] op_sel_hi:[0,1,1]
	ds_read_b32 v42, v75 offset:96
	v_pk_fma_f32 v[20:21], v[60:61], v[38:39], v[20:21] op_sel:[1,0,0] op_sel_hi:[1,1,1]
	v_pk_mul_f32 v[32:33], v[32:33], v[62:63] op_sel_hi:[1,0]
	v_pk_mul_f32 v[34:35], v[34:35], v[62:63] op_sel_hi:[1,0]
	v_add_f32_dpp v20, v20, v20 quad_perm:[1,0,3,2] row_mask:0xf bank_mask:0xf bound_ctrl:1
	v_pk_fma_f32 v[32:33], v[58:59], v[24:25], v[32:33]
	v_pk_fma_f32 v[34:35], v[60:61], v[26:27], v[34:35]
	v_add_f32_dpp v20, v20, v20 quad_perm:[2,3,0,1] row_mask:0xf bank_mask:0xf bound_ctrl:1
	ds_read_b128 v[4:7], v74 offset:4352
	ds_read_b128 v[8:11], v74 offset:4608
	v_add_f32_dpp v20, v20, v20 row_half_mirror row_mask:0xf bank_mask:0xf bound_ctrl:1
	ds_read_b128 v[12:15], v74 offset:4864
	ds_write_b32 v72, v21
	v_add_f32_dpp v20, v20, v20 row_mirror row_mask:0xf bank_mask:0xf bound_ctrl:1
	v_pk_fma_f32 v[58:59], v[28:29], v[20:21], v[32:33] op_sel_hi:[1,0,1]
	v_pk_fma_f32 v[60:61], v[30:31], v[20:21], v[34:35] op_sel_hi:[1,0,1]
	s_waitcnt lgkmcnt(7)
	v_pk_mul_f32 v[46:47], v[58:59], v[46:47] op_sel_hi:[0,1]
	ds_read_b128 v[20:23], v73 offset:5120
	v_pk_fma_f32 v[46:47], v[58:59], v[48:49], v[46:47] op_sel:[1,0,0] op_sel_hi:[1,1,1]
	ds_read_b128 v[36:39], v73 offset:5136
	v_pk_fma_f32 v[46:47], v[60:61], v[76:77], v[46:47] op_sel_hi:[0,1,1]
	ds_read_b32 v62, v75 offset:128
	v_pk_fma_f32 v[46:47], v[60:61], v[78:79], v[46:47] op_sel:[1,0,0] op_sel_hi:[1,1,1]
	v_pk_mul_f32 v[68:69], v[68:69], v[44:45] op_sel_hi:[1,0]
	v_pk_mul_f32 v[70:71], v[70:71], v[44:45] op_sel_hi:[1,0]
	v_add_f32_dpp v46, v46, v46 quad_perm:[1,0,3,2] row_mask:0xf bank_mask:0xf bound_ctrl:1
	v_pk_fma_f32 v[68:69], v[58:59], v[50:51], v[68:69]
	v_pk_fma_f32 v[70:71], v[60:61], v[52:53], v[70:71]
	v_add_f32_dpp v46, v46, v46 quad_perm:[2,3,0,1] row_mask:0xf bank_mask:0xf bound_ctrl:1
	ds_read_b128 v[24:27], v74 offset:5632
	ds_read_b128 v[28:31], v74 offset:5888
	v_add_f32_dpp v46, v46, v46 row_half_mirror row_mask:0xf bank_mask:0xf bound_ctrl:1
	ds_read_b128 v[32:35], v74 offset:6144
	ds_write_b32 v72, v47 offset:512
	v_add_f32_dpp v46, v46, v46 row_mirror row_mask:0xf bank_mask:0xf bound_ctrl:1
	v_pk_fma_f32 v[58:59], v[54:55], v[46:47], v[68:69] op_sel_hi:[1,0,1]
	v_pk_fma_f32 v[60:61], v[56:57], v[46:47], v[70:71] op_sel_hi:[1,0,1]
	s_waitcnt lgkmcnt(8)
	v_pk_mul_f32 v[0:1], v[58:59], v[0:1] op_sel_hi:[0,1]
	ds_read_b128 v[46:49], v73 offset:6400
	v_pk_fma_f32 v[0:1], v[58:59], v[2:3], v[0:1] op_sel:[1,0,0] op_sel_hi:[1,1,1]
	ds_read_b128 v[76:79], v73 offset:6416
	v_pk_fma_f32 v[0:1], v[60:61], v[16:17], v[0:1] op_sel_hi:[0,1,1]
	ds_read_b32 v44, v75 offset:160
	v_pk_fma_f32 v[0:1], v[60:61], v[18:19], v[0:1] op_sel:[1,0,0] op_sel_hi:[1,1,1]
	v_pk_mul_f32 v[12:13], v[12:13], v[42:43] op_sel_hi:[1,0]
	v_pk_mul_f32 v[14:15], v[14:15], v[42:43] op_sel_hi:[1,0]
	v_add_f32_dpp v0, v0, v0 quad_perm:[1,0,3,2] row_mask:0xf bank_mask:0xf bound_ctrl:1
	v_pk_fma_f32 v[12:13], v[58:59], v[4:5], v[12:13]
	v_pk_fma_f32 v[14:15], v[60:61], v[6:7], v[14:15]
	v_add_f32_dpp v0, v0, v0 quad_perm:[2,3,0,1] row_mask:0xf bank_mask:0xf bound_ctrl:1
	ds_read_b128 v[50:53], v74 offset:6912
	ds_read_b128 v[54:57], v74 offset:7168
	v_add_f32_dpp v0, v0, v0 row_half_mirror row_mask:0xf bank_mask:0xf bound_ctrl:1
	ds_read_b128 v[68:71], v74 offset:7424
	ds_write_b32 v72, v1 offset:1024
	v_add_f32_dpp v0, v0, v0 row_mirror row_mask:0xf bank_mask:0xf bound_ctrl:1
	v_pk_fma_f32 v[58:59], v[8:9], v[0:1], v[12:13] op_sel_hi:[1,0,1]
	v_pk_fma_f32 v[60:61], v[10:11], v[0:1], v[14:15] op_sel_hi:[1,0,1]
	s_waitcnt lgkmcnt(8)
; #define RW_LDS_WAIT(X) asm volatile("s_waitcnt lgkmcnt(0)" : "+v"(nk##X), "+v"(dd##X), "+v"(bb##X), "+v"(kp##X), "+v"(rr##X), "+v"(vv##X) :: "memory")
; DI void rwkv_scan_phase(int wv, const Params& P, LAS unsigned char* lds) {
;     ...
;                     RW_LDS_LOAD(B, 1); RW_STEP(A, 0); RW_LDS_WAIT(B);
;                     RW_LDS_LOAD(A, 2); RW_STEP(B, 1); RW_LDS_WAIT(A);
;                     RW_LDS_LOAD(B, 3); RW_STEP(A, 2); RW_LDS_WAIT(B);
;                     RW_LDS_LOAD(A, 4); RW_STEP(B, 3); RW_LDS_WAIT(A);
;                     RW_LDS_LOAD(B, 5); RW_STEP(A, 4); RW_LDS_WAIT(B);
;                     RW_LDS_LOAD(A, 6); RW_STEP(B, 5); RW_LDS_WAIT(A);
;                     RW_LDS_LOAD(B, 7); RW_STEP(A, 6); RW_LDS_WAIT(B);
;                     RW_LDS_LOAD(A, 8); RW_STEP(B, 7); RW_LDS_WAIT(A);
	v_pk_mul_f32 v[20:21], v[58:59], v[20:21] op_sel_hi:[0,1]
	ds_read_b128 v[0:3], v73 offset:7680
	v_pk_fma_f32 v[20:21], v[58:59], v[22:23], v[20:21] op_sel:[1,0,0] op_sel_hi:[1,1,1]
	ds_read_b128 v[16:19], v73 offset:7696
	v_pk_fma_f32 v[20:21], v[60:61], v[36:37], v[20:21] op_sel_hi:[0,1,1]
	ds_read_b32 v42, v75 offset:192
	v_pk_fma_f32 v[20:21], v[60:61], v[38:39], v[20:21] op_sel:[1,0,0] op_sel_hi:[1,1,1]
	v_pk_mul_f32 v[32:33], v[32:33], v[62:63] op_sel_hi:[1,0]
	v_pk_mul_f32 v[34:35], v[34:35], v[62:63] op_sel_hi:[1,0]
	v_add_f32_dpp v20, v20, v20 quad_perm:[1,0,3,2] row_mask:0xf bank_mask:0xf bound_ctrl:1
	v_pk_fma_f32 v[32:33], v[58:59], v[24:25], v[32:33]
	v_pk_fma_f32 v[34:35], v[60:61], v[26:27], v[34:35]
	v_add_f32_dpp v20, v20, v20 quad_perm:[2,3,0,1] row_mask:0xf bank_mask:0xf bound_ctrl:1
	ds_read_b128 v[4:7], v74 offset:8192
	ds_read_b128 v[8:11], v74 offset:8448
	v_add_f32_dpp v20, v20, v20 row_half_mirror row_mask:0xf bank_mask:0xf bound_ctrl:1
	ds_read_b128 v[12:15], v74 offset:8704
	ds_write_b32 v72, v21 offset:1536
	v_add_f32_dpp v20, v20, v20 row_mirror row_mask:0xf bank_mask:0xf bound_ctrl:1
	v_pk_fma_f32 v[58:59], v[28:29], v[20:21], v[32:33] op_sel_hi:[1,0,1]
	v_pk_fma_f32 v[60:61], v[30:31], v[20:21], v[34:35] op_sel_hi:[1,0,1]
	s_waitcnt lgkmcnt(8)
	v_pk_mul_f32 v[46:47], v[58:59], v[46:47] op_sel_hi:[0,1]
	ds_read_b128 v[20:23], v73 offset:8960
	v_pk_fma_f32 v[46:47], v[58:59], v[48:49], v[46:47] op_sel:[1,0,0] op_sel_hi:[1,1,1]
	ds_read_b128 v[36:39], v73 offset:8976
	v_pk_fma_f32 v[46:47], v[60:61], v[76:77], v[46:47] op_sel_hi:[0,1,1]
	ds_read_b32 v62, v75 offset:224
	v_pk_fma_f32 v[46:47], v[60:61], v[78:79], v[46:47] op_sel:[1,0,0] op_sel_hi:[1,1,1]
	v_pk_mul_f32 v[68:69], v[68:69], v[44:45] op_sel_hi:[1,0]
	v_pk_mul_f32 v[70:71], v[70:71], v[44:45] op_sel_hi:[1,0]
	v_add_f32_dpp v46, v46, v46 quad_perm:[1,0,3,2] row_mask:0xf bank_mask:0xf bound_ctrl:1
	v_pk_fma_f32 v[68:69], v[58:59], v[50:51], v[68:69]
	v_pk_fma_f32 v[70:71], v[60:61], v[52:53], v[70:71]
	v_add_f32_dpp v46, v46, v46 quad_perm:[2,3,0,1] row_mask:0xf bank_mask:0xf bound_ctrl:1
	ds_read_b128 v[24:27], v74 offset:9472
	ds_read_b128 v[28:31], v74 offset:9728
	v_add_f32_dpp v46, v46, v46 row_half_mirror row_mask:0xf bank_mask:0xf bound_ctrl:1
	ds_read_b128 v[32:35], v74 offset:9984
	ds_write_b32 v72, v47 offset:2048
	v_add_f32_dpp v46, v46, v46 row_mirror row_mask:0xf bank_mask:0xf bound_ctrl:1
	v_pk_fma_f32 v[58:59], v[54:55], v[46:47], v[68:69] op_sel_hi:[1,0,1]
	v_pk_fma_f32 v[60:61], v[56:57], v[46:47], v[70:71] op_sel_hi:[1,0,1]
	s_waitcnt lgkmcnt(8)
	v_pk_mul_f32 v[0:1], v[58:59], v[0:1] op_sel_hi:[0,1]
	ds_read_b128 v[46:49], v73 offset:10240
	v_pk_fma_f32 v[0:1], v[58:59], v[2:3], v[0:1] op_sel:[1,0,0] op_sel_hi:[1,1,1]
	ds_read_b128 v[76:79], v73 offset:10256
	v_pk_fma_f32 v[0:1], v[60:61], v[16:17], v[0:1] op_sel_hi:[0,1,1]
	ds_read_b32 v44, v75 offset:256
	v_pk_fma_f32 v[0:1], v[60:61], v[18:19], v[0:1] op_sel:[1,0,0] op_sel_hi:[1,1,1]
	v_pk_mul_f32 v[12:13], v[12:13], v[42:43] op_sel_hi:[1,0]
	v_pk_mul_f32 v[14:15], v[14:15], v[42:43] op_sel_hi:[1,0]
	v_add_f32_dpp v0, v0, v0 quad_perm:[1,0,3,2] row_mask:0xf bank_mask:0xf bound_ctrl:1
	v_pk_fma_f32 v[12:13], v[58:59], v[4:5], v[12:13]
	v_pk_fma_f32 v[14:15], v[60:61], v[6:7], v[14:15]
	v_add_f32_dpp v0, v0, v0 quad_perm:[2,3,0,1] row_mask:0xf bank_mask:0xf bound_ctrl:1
	ds_read_b128 v[50:53], v74 offset:10752
	ds_read_b128 v[54:57], v74 offset:11008
	v_add_f32_dpp v0, v0, v0 row_half_mirror row_mask:0xf bank_mask:0xf bound_ctrl:1
	ds_read_b128 v[68:71], v74 offset:11264
	ds_write_b32 v72, v1 offset:2560
	v_add_f32_dpp v0, v0, v0 row_mirror row_mask:0xf bank_mask:0xf bound_ctrl:1
	v_pk_fma_f32 v[58:59], v[8:9], v[0:1], v[12:13] op_sel_hi:[1,0,1]
	v_pk_fma_f32 v[60:61], v[10:11], v[0:1], v[14:15] op_sel_hi:[1,0,1]
	s_waitcnt lgkmcnt(8)
	v_pk_mul_f32 v[20:21], v[58:59], v[20:21] op_sel_hi:[0,1]
	ds_read_b128 v[0:3], v73 offset:11520
	v_pk_fma_f32 v[20:21], v[58:59], v[22:23], v[20:21] op_sel:[1,0,0] op_sel_hi:[1,1,1]
	ds_read_b128 v[16:19], v73 offset:11536
	v_pk_fma_f32 v[20:21], v[60:61], v[36:37], v[20:21] op_sel_hi:[0,1,1]
	ds_read_b32 v42, v75 offset:288
	v_pk_fma_f32 v[20:21], v[60:61], v[38:39], v[20:21] op_sel:[1,0,0] op_sel_hi:[1,1,1]
	v_pk_mul_f32 v[32:33], v[32:33], v[62:63] op_sel_hi:[1,0]
	v_pk_mul_f32 v[34:35], v[34:35], v[62:63] op_sel_hi:[1,0]
	v_add_f32_dpp v20, v20, v20 quad_perm:[1,0,3,2] row_mask:0xf bank_mask:0xf bound_ctrl:1
	v_pk_fma_f32 v[32:33], v[58:59], v[24:25], v[32:33]
	v_pk_fma_f32 v[34:35], v[60:61], v[26:27], v[34:35]
	v_add_f32_dpp v20, v20, v20 quad_perm:[2,3,0,1] row_mask:0xf bank_mask:0xf bound_ctrl:1
	ds_read_b128 v[4:7], v74 offset:12032
	ds_read_b128 v[8:11], v74 offset:12288
	v_add_f32_dpp v20, v20, v20 row_half_mirror row_mask:0xf bank_mask:0xf bound_ctrl:1
	ds_read_b128 v[12:15], v74 offset:12544
	ds_write_b32 v72, v21 offset:3072
	v_add_f32_dpp v20, v20, v20 row_mirror row_mask:0xf bank_mask:0xf bound_ctrl:1
	v_pk_fma_f32 v[58:59], v[28:29], v[20:21], v[32:33] op_sel_hi:[1,0,1]
	v_pk_fma_f32 v[60:61], v[30:31], v[20:21], v[34:35] op_sel_hi:[1,0,1]
	s_waitcnt lgkmcnt(8)
; #define RW_LDS_WAIT(X) asm volatile("s_waitcnt lgkmcnt(0)" : "+v"(nk##X), "+v"(dd##X), "+v"(bb##X), "+v"(kp##X), "+v"(rr##X), "+v"(vv##X) :: "memory")
; DI void rwkv_scan_phase(int wv, const Params& P, LAS unsigned char* lds) {
;     ...
;                     RW_LDS_LOAD(A, 8); RW_STEP(B, 7); RW_LDS_WAIT(A);
;                     RW_LDS_LOAD(B, 9); RW_STEP(A, 8); RW_LDS_WAIT(B);
;                     RW_LDS_LOAD(A, 10); RW_STEP(B, 9); RW_LDS_WAIT(A);
;                     RW_LDS_LOAD(B, 11); RW_STEP(A, 10); RW_LDS_WAIT(B);
;                     RW_LDS_LOAD(A, 12); RW_STEP(B, 11); RW_LDS_WAIT(A);
;                     RW_LDS_LOAD(B, 13); RW_STEP(A, 12); RW_LDS_WAIT(B);
;                     RW_LDS_LOAD(A, 14); RW_STEP(B, 13); RW_LDS_WAIT(A);
	v_pk_mul_f32 v[46:47], v[58:59], v[46:47] op_sel_hi:[0,1]
	ds_read_b128 v[20:23], v73 offset:12800
	v_pk_fma_f32 v[46:47], v[58:59], v[48:49], v[46:47] op_sel:[1,0,0] op_sel_hi:[1,1,1]
	ds_read_b128 v[36:39], v73 offset:12816
	v_pk_fma_f32 v[46:47], v[60:61], v[76:77], v[46:47] op_sel_hi:[0,1,1]
	ds_read_b32 v62, v75 offset:320
	v_pk_fma_f32 v[46:47], v[60:61], v[78:79], v[46:47] op_sel:[1,0,0] op_sel_hi:[1,1,1]
	v_pk_mul_f32 v[68:69], v[68:69], v[44:45] op_sel_hi:[1,0]
	v_pk_mul_f32 v[70:71], v[70:71], v[44:45] op_sel_hi:[1,0]
	v_add_f32_dpp v46, v46, v46 quad_perm:[1,0,3,2] row_mask:0xf bank_mask:0xf bound_ctrl:1
	v_pk_fma_f32 v[68:69], v[58:59], v[50:51], v[68:69]
	v_pk_fma_f32 v[70:71], v[60:61], v[52:53], v[70:71]
	v_add_f32_dpp v46, v46, v46 quad_perm:[2,3,0,1] row_mask:0xf bank_mask:0xf bound_ctrl:1
	ds_read_b128 v[24:27], v74 offset:13312
	ds_read_b128 v[28:31], v74 offset:13568
	v_add_f32_dpp v46, v46, v46 row_half_mirror row_mask:0xf bank_mask:0xf bound_ctrl:1
	ds_read_b128 v[32:35], v74 offset:13824
	ds_write_b32 v72, v47 offset:3584
	v_add_f32_dpp v46, v46, v46 row_mirror row_mask:0xf bank_mask:0xf bound_ctrl:1
	v_pk_fma_f32 v[58:59], v[54:55], v[46:47], v[68:69] op_sel_hi:[1,0,1]
	v_pk_fma_f32 v[60:61], v[56:57], v[46:47], v[70:71] op_sel_hi:[1,0,1]
	s_waitcnt lgkmcnt(8)
	v_pk_mul_f32 v[0:1], v[58:59], v[0:1] op_sel_hi:[0,1]
	ds_read_b128 v[46:49], v73 offset:14080
	v_pk_fma_f32 v[0:1], v[58:59], v[2:3], v[0:1] op_sel:[1,0,0] op_sel_hi:[1,1,1]
	ds_read_b128 v[76:79], v73 offset:14096
	v_pk_fma_f32 v[0:1], v[60:61], v[16:17], v[0:1] op_sel_hi:[0,1,1]
	ds_read_b32 v44, v75 offset:352
	v_pk_fma_f32 v[0:1], v[60:61], v[18:19], v[0:1] op_sel:[1,0,0] op_sel_hi:[1,1,1]
	v_pk_mul_f32 v[12:13], v[12:13], v[42:43] op_sel_hi:[1,0]
	v_pk_mul_f32 v[14:15], v[14:15], v[42:43] op_sel_hi:[1,0]
	v_add_f32_dpp v0, v0, v0 quad_perm:[1,0,3,2] row_mask:0xf bank_mask:0xf bound_ctrl:1
	v_pk_fma_f32 v[12:13], v[58:59], v[4:5], v[12:13]
	v_pk_fma_f32 v[14:15], v[60:61], v[6:7], v[14:15]
	v_add_f32_dpp v0, v0, v0 quad_perm:[2,3,0,1] row_mask:0xf bank_mask:0xf bound_ctrl:1
	ds_read_b128 v[50:53], v74 offset:14592
	ds_read_b128 v[54:57], v74 offset:14848
	v_add_f32_dpp v0, v0, v0 row_half_mirror row_mask:0xf bank_mask:0xf bound_ctrl:1
	ds_read_b128 v[68:71], v74 offset:15104
	ds_write_b32 v72, v1 offset:4096
	v_add_f32_dpp v0, v0, v0 row_mirror row_mask:0xf bank_mask:0xf bound_ctrl:1
	v_pk_fma_f32 v[58:59], v[8:9], v[0:1], v[12:13] op_sel_hi:[1,0,1]
	v_pk_fma_f32 v[60:61], v[10:11], v[0:1], v[14:15] op_sel_hi:[1,0,1]
	s_waitcnt lgkmcnt(8)
	v_pk_mul_f32 v[20:21], v[58:59], v[20:21] op_sel_hi:[0,1]
	ds_read_b128 v[0:3], v73 offset:15360
	v_pk_fma_f32 v[20:21], v[58:59], v[22:23], v[20:21] op_sel:[1,0,0] op_sel_hi:[1,1,1]
	ds_read_b128 v[16:19], v73 offset:15376
	v_pk_fma_f32 v[20:21], v[60:61], v[36:37], v[20:21] op_sel_hi:[0,1,1]
	ds_read_b32 v42, v75 offset:384
	v_pk_fma_f32 v[20:21], v[60:61], v[38:39], v[20:21] op_sel:[1,0,0] op_sel_hi:[1,1,1]
	v_pk_mul_f32 v[32:33], v[32:33], v[62:63] op_sel_hi:[1,0]
	v_pk_mul_f32 v[34:35], v[34:35], v[62:63] op_sel_hi:[1,0]
	v_add_f32_dpp v20, v20, v20 quad_perm:[1,0,3,2] row_mask:0xf bank_mask:0xf bound_ctrl:1
	v_pk_fma_f32 v[32:33], v[58:59], v[24:25], v[32:33]
	v_pk_fma_f32 v[34:35], v[60:61], v[26:27], v[34:35]
	v_add_f32_dpp v20, v20, v20 quad_perm:[2,3,0,1] row_mask:0xf bank_mask:0xf bound_ctrl:1
	ds_read_b128 v[4:7], v74 offset:15872
	ds_read_b128 v[8:11], v74 offset:16128
	v_add_f32_dpp v20, v20, v20 row_half_mirror row_mask:0xf bank_mask:0xf bound_ctrl:1
	ds_read_b128 v[12:15], v74 offset:16384
	ds_write_b32 v72, v21 offset:4608
	v_add_f32_dpp v20, v20, v20 row_mirror row_mask:0xf bank_mask:0xf bound_ctrl:1
	v_pk_fma_f32 v[58:59], v[28:29], v[20:21], v[32:33] op_sel_hi:[1,0,1]
	v_pk_fma_f32 v[60:61], v[30:31], v[20:21], v[34:35] op_sel_hi:[1,0,1]
	s_waitcnt lgkmcnt(8)
	v_pk_mul_f32 v[46:47], v[58:59], v[46:47] op_sel_hi:[0,1]
	ds_read_b128 v[20:23], v73 offset:16640
	v_pk_fma_f32 v[46:47], v[58:59], v[48:49], v[46:47] op_sel:[1,0,0] op_sel_hi:[1,1,1]
	ds_read_b128 v[36:39], v73 offset:16656
	v_pk_fma_f32 v[46:47], v[60:61], v[76:77], v[46:47] op_sel_hi:[0,1,1]
	ds_read_b32 v62, v75 offset:416
	v_pk_fma_f32 v[46:47], v[60:61], v[78:79], v[46:47] op_sel:[1,0,0] op_sel_hi:[1,1,1]
	v_pk_mul_f32 v[68:69], v[68:69], v[44:45] op_sel_hi:[1,0]
	v_pk_mul_f32 v[70:71], v[70:71], v[44:45] op_sel_hi:[1,0]
	v_add_f32_dpp v46, v46, v46 quad_perm:[1,0,3,2] row_mask:0xf bank_mask:0xf bound_ctrl:1
	v_pk_fma_f32 v[68:69], v[58:59], v[50:51], v[68:69]
	v_pk_fma_f32 v[70:71], v[60:61], v[52:53], v[70:71]
	v_add_f32_dpp v46, v46, v46 quad_perm:[2,3,0,1] row_mask:0xf bank_mask:0xf bound_ctrl:1
	ds_read_b128 v[24:27], v74 offset:17152
	ds_read_b128 v[28:31], v74 offset:17408
	v_add_f32_dpp v46, v46, v46 row_half_mirror row_mask:0xf bank_mask:0xf bound_ctrl:1
	ds_read_b128 v[32:35], v74 offset:17664
	ds_write_b32 v72, v47 offset:5120
	v_add_f32_dpp v46, v46, v46 row_mirror row_mask:0xf bank_mask:0xf bound_ctrl:1
	v_pk_fma_f32 v[58:59], v[54:55], v[46:47], v[68:69] op_sel_hi:[1,0,1]
	v_pk_fma_f32 v[60:61], v[56:57], v[46:47], v[70:71] op_sel_hi:[1,0,1]
	s_waitcnt lgkmcnt(8)
; #define RW_LDS_WAIT(X) asm volatile("s_waitcnt lgkmcnt(0)" : "+v"(nk##X), "+v"(dd##X), "+v"(bb##X), "+v"(kp##X), "+v"(rr##X), "+v"(vv##X) :: "memory")
; DI void rwkv_scan_phase(int wv, const Params& P, LAS unsigned char* lds) {
;     ...
;                     RW_LDS_LOAD(B, 11); RW_STEP(A, 10); RW_LDS_WAIT(B);
;                     RW_LDS_LOAD(A, 12); RW_STEP(B, 11); RW_LDS_WAIT(A);
;                     RW_LDS_LOAD(B, 13); RW_STEP(A, 12); RW_LDS_WAIT(B);
;                     RW_LDS_LOAD(A, 14); RW_STEP(B, 13); RW_LDS_WAIT(A);
;                     RW_LDS_LOAD(B, 15); RW_STEP(A, 14); RW_LDS_WAIT(B);
;                     RW_LDS_LOAD(A, 16); RW_STEP(B, 15); RW_LDS_WAIT(A);
;                 }
	v_pk_mul_f32 v[0:1], v[58:59], v[0:1] op_sel_hi:[0,1]
	ds_read_b128 v[46:49], v73 offset:17920
	v_pk_fma_f32 v[0:1], v[58:59], v[2:3], v[0:1] op_sel:[1,0,0] op_sel_hi:[1,1,1]
	ds_read_b128 v[76:79], v73 offset:17936
	v_pk_fma_f32 v[0:1], v[60:61], v[16:17], v[0:1] op_sel_hi:[0,1,1]
	ds_read_b32 v44, v75 offset:448
	v_pk_fma_f32 v[0:1], v[60:61], v[18:19], v[0:1] op_sel:[1,0,0] op_sel_hi:[1,1,1]
	v_pk_mul_f32 v[12:13], v[12:13], v[42:43] op_sel_hi:[1,0]
	v_pk_mul_f32 v[14:15], v[14:15], v[42:43] op_sel_hi:[1,0]
	v_add_f32_dpp v0, v0, v0 quad_perm:[1,0,3,2] row_mask:0xf bank_mask:0xf bound_ctrl:1
	v_pk_fma_f32 v[12:13], v[58:59], v[4:5], v[12:13]
	v_pk_fma_f32 v[14:15], v[60:61], v[6:7], v[14:15]
	v_add_f32_dpp v0, v0, v0 quad_perm:[2,3,0,1] row_mask:0xf bank_mask:0xf bound_ctrl:1
	ds_read_b128 v[50:53], v74 offset:18432
	ds_read_b128 v[54:57], v74 offset:18688
	v_add_f32_dpp v0, v0, v0 row_half_mirror row_mask:0xf bank_mask:0xf bound_ctrl:1
	ds_read_b128 v[68:71], v74 offset:18944
	ds_write_b32 v72, v1 offset:5632
	v_add_f32_dpp v0, v0, v0 row_mirror row_mask:0xf bank_mask:0xf bound_ctrl:1
	v_pk_fma_f32 v[58:59], v[8:9], v[0:1], v[12:13] op_sel_hi:[1,0,1]
	v_pk_fma_f32 v[60:61], v[10:11], v[0:1], v[14:15] op_sel_hi:[1,0,1]
	s_waitcnt lgkmcnt(8)
	v_pk_mul_f32 v[20:21], v[58:59], v[20:21] op_sel_hi:[0,1]
	ds_read_b128 v[0:3], v73 offset:19200
	v_pk_fma_f32 v[20:21], v[58:59], v[22:23], v[20:21] op_sel:[1,0,0] op_sel_hi:[1,1,1]
	ds_read_b128 v[16:19], v73 offset:19216
	v_pk_fma_f32 v[20:21], v[60:61], v[36:37], v[20:21] op_sel_hi:[0,1,1]
	ds_read_b32 v42, v75 offset:480
	v_pk_fma_f32 v[20:21], v[60:61], v[38:39], v[20:21] op_sel:[1,0,0] op_sel_hi:[1,1,1]
	v_pk_mul_f32 v[32:33], v[32:33], v[62:63] op_sel_hi:[1,0]
	v_pk_mul_f32 v[34:35], v[34:35], v[62:63] op_sel_hi:[1,0]
	v_add_f32_dpp v20, v20, v20 quad_perm:[1,0,3,2] row_mask:0xf bank_mask:0xf bound_ctrl:1
	v_pk_fma_f32 v[32:33], v[58:59], v[24:25], v[32:33]
	v_pk_fma_f32 v[34:35], v[60:61], v[26:27], v[34:35]
	v_add_f32_dpp v20, v20, v20 quad_perm:[2,3,0,1] row_mask:0xf bank_mask:0xf bound_ctrl:1
	ds_read_b128 v[4:7], v74 offset:19712
	ds_read_b128 v[8:11], v74 offset:19968
	v_add_f32_dpp v20, v20, v20 row_half_mirror row_mask:0xf bank_mask:0xf bound_ctrl:1
	ds_read_b128 v[12:15], v74 offset:20224
	ds_write_b32 v72, v21 offset:6144
	v_add_f32_dpp v20, v20, v20 row_mirror row_mask:0xf bank_mask:0xf bound_ctrl:1
	v_pk_fma_f32 v[58:59], v[28:29], v[20:21], v[32:33] op_sel_hi:[1,0,1]
	v_pk_fma_f32 v[60:61], v[30:31], v[20:21], v[34:35] op_sel_hi:[1,0,1]
	s_waitcnt lgkmcnt(8)
	v_pk_mul_f32 v[46:47], v[58:59], v[46:47] op_sel_hi:[0,1]
	ds_read_b128 v[20:23], v73 offset:20480
	v_pk_fma_f32 v[46:47], v[58:59], v[48:49], v[46:47] op_sel:[1,0,0] op_sel_hi:[1,1,1]
	ds_read_b128 v[36:39], v73 offset:20496
	v_pk_fma_f32 v[46:47], v[60:61], v[76:77], v[46:47] op_sel_hi:[0,1,1]
	ds_read_b32 v62, v75 offset:512
	v_pk_fma_f32 v[46:47], v[60:61], v[78:79], v[46:47] op_sel:[1,0,0] op_sel_hi:[1,1,1]
	v_pk_mul_f32 v[68:69], v[68:69], v[44:45] op_sel_hi:[1,0]
	v_pk_mul_f32 v[70:71], v[70:71], v[44:45] op_sel_hi:[1,0]
	v_add_f32_dpp v46, v46, v46 quad_perm:[1,0,3,2] row_mask:0xf bank_mask:0xf bound_ctrl:1
	v_pk_fma_f32 v[68:69], v[58:59], v[50:51], v[68:69]
	v_pk_fma_f32 v[70:71], v[60:61], v[52:53], v[70:71]
	v_add_f32_dpp v46, v46, v46 quad_perm:[2,3,0,1] row_mask:0xf bank_mask:0xf bound_ctrl:1
	ds_read_b128 v[24:27], v74 offset:20992
	ds_read_b128 v[28:31], v74 offset:21248
	v_add_f32_dpp v46, v46, v46 row_half_mirror row_mask:0xf bank_mask:0xf bound_ctrl:1
	ds_read_b128 v[32:35], v74 offset:21504
	ds_write_b32 v72, v47 offset:6656
	v_add_f32_dpp v46, v46, v46 row_mirror row_mask:0xf bank_mask:0xf bound_ctrl:1
	v_pk_fma_f32 v[58:59], v[54:55], v[46:47], v[68:69] op_sel_hi:[1,0,1]
	v_pk_fma_f32 v[60:61], v[56:57], v[46:47], v[70:71] op_sel_hi:[1,0,1]
	s_waitcnt lgkmcnt(8)
	v_pk_mul_f32 v[0:1], v[58:59], v[0:1] op_sel_hi:[0,1]
	ds_read_b128 v[46:49], v73 offset:21760
	v_pk_fma_f32 v[0:1], v[58:59], v[2:3], v[0:1] op_sel:[1,0,0] op_sel_hi:[1,1,1]
	ds_read_b128 v[76:79], v73 offset:21776
	v_pk_fma_f32 v[0:1], v[60:61], v[16:17], v[0:1] op_sel_hi:[0,1,1]
	ds_read_b32 v44, v75 offset:544
	v_pk_fma_f32 v[0:1], v[60:61], v[18:19], v[0:1] op_sel:[1,0,0] op_sel_hi:[1,1,1]
	v_pk_mul_f32 v[12:13], v[12:13], v[42:43] op_sel_hi:[1,0]
	v_pk_mul_f32 v[14:15], v[14:15], v[42:43] op_sel_hi:[1,0]
	v_add_f32_dpp v0, v0, v0 quad_perm:[1,0,3,2] row_mask:0xf bank_mask:0xf bound_ctrl:1
	v_pk_fma_f32 v[12:13], v[58:59], v[4:5], v[12:13]
	v_pk_fma_f32 v[14:15], v[60:61], v[6:7], v[14:15]
	v_add_f32_dpp v0, v0, v0 quad_perm:[2,3,0,1] row_mask:0xf bank_mask:0xf bound_ctrl:1
	ds_read_b128 v[50:53], v74 offset:22272
	ds_read_b128 v[54:57], v74 offset:22528
	v_add_f32_dpp v0, v0, v0 row_half_mirror row_mask:0xf bank_mask:0xf bound_ctrl:1
	ds_read_b128 v[68:71], v74 offset:22784
	ds_write_b32 v72, v1 offset:7168
	v_add_f32_dpp v0, v0, v0 row_mirror row_mask:0xf bank_mask:0xf bound_ctrl:1
	v_pk_fma_f32 v[58:59], v[8:9], v[0:1], v[12:13] op_sel_hi:[1,0,1]
	v_pk_fma_f32 v[60:61], v[10:11], v[0:1], v[14:15] op_sel_hi:[1,0,1]
	s_waitcnt lgkmcnt(8)
	v_pk_mul_f32 v[20:21], v[58:59], v[20:21] op_sel_hi:[0,1]
	ds_read_b128 v[0:3], v73 offset:23040
	v_pk_fma_f32 v[20:21], v[58:59], v[22:23], v[20:21] op_sel:[1,0,0] op_sel_hi:[1,1,1]
	ds_read_b128 v[16:19], v73 offset:23056
	v_pk_fma_f32 v[20:21], v[60:61], v[36:37], v[20:21] op_sel_hi:[0,1,1]
	ds_read_b32 v42, v75 offset:576
	v_pk_fma_f32 v[20:21], v[60:61], v[38:39], v[20:21] op_sel:[1,0,0] op_sel_hi:[1,1,1]
	v_pk_mul_f32 v[32:33], v[32:33], v[62:63] op_sel_hi:[1,0]
	v_pk_mul_f32 v[34:35], v[34:35], v[62:63] op_sel_hi:[1,0]
	v_add_f32_dpp v20, v20, v20 quad_perm:[1,0,3,2] row_mask:0xf bank_mask:0xf bound_ctrl:1
	v_pk_fma_f32 v[32:33], v[58:59], v[24:25], v[32:33]
	v_pk_fma_f32 v[34:35], v[60:61], v[26:27], v[34:35]
	v_add_f32_dpp v20, v20, v20 quad_perm:[2,3,0,1] row_mask:0xf bank_mask:0xf bound_ctrl:1
	ds_read_b128 v[4:7], v74 offset:23552
	ds_read_b128 v[8:11], v74 offset:23808
	v_add_f32_dpp v20, v20, v20 row_half_mirror row_mask:0xf bank_mask:0xf bound_ctrl:1
	ds_read_b128 v[12:15], v74 offset:24064
	ds_write_b32 v72, v21 offset:7680
	v_add_f32_dpp v20, v20, v20 row_mirror row_mask:0xf bank_mask:0xf bound_ctrl:1
	v_pk_fma_f32 v[58:59], v[28:29], v[20:21], v[32:33] op_sel_hi:[1,0,1]
	v_pk_fma_f32 v[60:61], v[30:31], v[20:21], v[34:35] op_sel_hi:[1,0,1]
	s_waitcnt lgkmcnt(8)
	v_pk_mul_f32 v[46:47], v[58:59], v[46:47] op_sel_hi:[0,1]
	ds_read_b128 v[20:23], v73 offset:24320
	v_pk_fma_f32 v[46:47], v[58:59], v[48:49], v[46:47] op_sel:[1,0,0] op_sel_hi:[1,1,1]
	ds_read_b128 v[36:39], v73 offset:24336
	v_pk_fma_f32 v[46:47], v[60:61], v[76:77], v[46:47] op_sel_hi:[0,1,1]
	ds_read_b32 v62, v75 offset:608
	v_pk_fma_f32 v[46:47], v[60:61], v[78:79], v[46:47] op_sel:[1,0,0] op_sel_hi:[1,1,1]
	v_pk_mul_f32 v[68:69], v[68:69], v[44:45] op_sel_hi:[1,0]
	v_pk_mul_f32 v[70:71], v[70:71], v[44:45] op_sel_hi:[1,0]
	v_add_f32_dpp v46, v46, v46 quad_perm:[1,0,3,2] row_mask:0xf bank_mask:0xf bound_ctrl:1
	v_pk_fma_f32 v[68:69], v[58:59], v[50:51], v[68:69]
	v_pk_fma_f32 v[70:71], v[60:61], v[52:53], v[70:71]
	v_add_f32_dpp v46, v46, v46 quad_perm:[2,3,0,1] row_mask:0xf bank_mask:0xf bound_ctrl:1
	ds_read_b128 v[24:27], v74 offset:24832
	ds_read_b128 v[28:31], v74 offset:25088
	v_add_f32_dpp v46, v46, v46 row_half_mirror row_mask:0xf bank_mask:0xf bound_ctrl:1
	ds_read_b128 v[32:35], v74 offset:25344
	ds_write_b32 v72, v47 offset:8192
	v_add_f32_dpp v46, v46, v46 row_mirror row_mask:0xf bank_mask:0xf bound_ctrl:1
	v_pk_fma_f32 v[58:59], v[54:55], v[46:47], v[68:69] op_sel_hi:[1,0,1]
	v_pk_fma_f32 v[60:61], v[56:57], v[46:47], v[70:71] op_sel_hi:[1,0,1]
	s_waitcnt lgkmcnt(8)
	v_pk_mul_f32 v[0:1], v[58:59], v[0:1] op_sel_hi:[0,1]
	ds_read_b128 v[46:49], v73 offset:25600
	v_pk_fma_f32 v[0:1], v[58:59], v[2:3], v[0:1] op_sel:[1,0,0] op_sel_hi:[1,1,1]
	ds_read_b128 v[76:79], v73 offset:25616
	v_pk_fma_f32 v[0:1], v[60:61], v[16:17], v[0:1] op_sel_hi:[0,1,1]
	ds_read_b32 v44, v75 offset:640
	v_pk_fma_f32 v[0:1], v[60:61], v[18:19], v[0:1] op_sel:[1,0,0] op_sel_hi:[1,1,1]
	v_pk_mul_f32 v[12:13], v[12:13], v[42:43] op_sel_hi:[1,0]
	v_pk_mul_f32 v[14:15], v[14:15], v[42:43] op_sel_hi:[1,0]
	v_add_f32_dpp v0, v0, v0 quad_perm:[1,0,3,2] row_mask:0xf bank_mask:0xf bound_ctrl:1
	v_pk_fma_f32 v[12:13], v[58:59], v[4:5], v[12:13]
	v_pk_fma_f32 v[14:15], v[60:61], v[6:7], v[14:15]
	v_add_f32_dpp v0, v0, v0 quad_perm:[2,3,0,1] row_mask:0xf bank_mask:0xf bound_ctrl:1
	ds_read_b128 v[50:53], v74 offset:26112
	ds_read_b128 v[54:57], v74 offset:26368
	v_add_f32_dpp v0, v0, v0 row_half_mirror row_mask:0xf bank_mask:0xf bound_ctrl:1
	ds_read_b128 v[68:71], v74 offset:26624
	ds_write_b32 v72, v1 offset:8704
	v_add_f32_dpp v0, v0, v0 row_mirror row_mask:0xf bank_mask:0xf bound_ctrl:1
	v_pk_fma_f32 v[58:59], v[8:9], v[0:1], v[12:13] op_sel_hi:[1,0,1]
	v_pk_fma_f32 v[60:61], v[10:11], v[0:1], v[14:15] op_sel_hi:[1,0,1]
	s_waitcnt lgkmcnt(8)
	v_pk_mul_f32 v[20:21], v[58:59], v[20:21] op_sel_hi:[0,1]
	ds_read_b128 v[0:3], v73 offset:26880
	v_pk_fma_f32 v[20:21], v[58:59], v[22:23], v[20:21] op_sel:[1,0,0] op_sel_hi:[1,1,1]
	ds_read_b128 v[16:19], v73 offset:26896
	v_pk_fma_f32 v[20:21], v[60:61], v[36:37], v[20:21] op_sel_hi:[0,1,1]
	ds_read_b32 v42, v75 offset:672
	v_pk_fma_f32 v[20:21], v[60:61], v[38:39], v[20:21] op_sel:[1,0,0] op_sel_hi:[1,1,1]
	v_pk_mul_f32 v[32:33], v[32:33], v[62:63] op_sel_hi:[1,0]
	v_pk_mul_f32 v[34:35], v[34:35], v[62:63] op_sel_hi:[1,0]
	v_add_f32_dpp v20, v20, v20 quad_perm:[1,0,3,2] row_mask:0xf bank_mask:0xf bound_ctrl:1
	v_pk_fma_f32 v[32:33], v[58:59], v[24:25], v[32:33]
	v_pk_fma_f32 v[34:35], v[60:61], v[26:27], v[34:35]
	v_add_f32_dpp v20, v20, v20 quad_perm:[2,3,0,1] row_mask:0xf bank_mask:0xf bound_ctrl:1
	ds_read_b128 v[4:7], v74 offset:27392
	ds_read_b128 v[8:11], v74 offset:27648
	v_add_f32_dpp v20, v20, v20 row_half_mirror row_mask:0xf bank_mask:0xf bound_ctrl:1
	ds_read_b128 v[12:15], v74 offset:27904
	ds_write_b32 v72, v21 offset:9216
	v_add_f32_dpp v20, v20, v20 row_mirror row_mask:0xf bank_mask:0xf bound_ctrl:1
	v_pk_fma_f32 v[58:59], v[28:29], v[20:21], v[32:33] op_sel_hi:[1,0,1]
	v_pk_fma_f32 v[60:61], v[30:31], v[20:21], v[34:35] op_sel_hi:[1,0,1]
	s_waitcnt lgkmcnt(8)
	v_pk_mul_f32 v[46:47], v[58:59], v[46:47] op_sel_hi:[0,1]
	ds_read_b128 v[20:23], v73 offset:28160
	v_pk_fma_f32 v[46:47], v[58:59], v[48:49], v[46:47] op_sel:[1,0,0] op_sel_hi:[1,1,1]
	ds_read_b128 v[36:39], v73 offset:28176
	v_pk_fma_f32 v[46:47], v[60:61], v[76:77], v[46:47] op_sel_hi:[0,1,1]
	ds_read_b32 v62, v75 offset:704
	v_pk_fma_f32 v[46:47], v[60:61], v[78:79], v[46:47] op_sel:[1,0,0] op_sel_hi:[1,1,1]
	v_pk_mul_f32 v[68:69], v[68:69], v[44:45] op_sel_hi:[1,0]
	v_pk_mul_f32 v[70:71], v[70:71], v[44:45] op_sel_hi:[1,0]
	v_add_f32_dpp v46, v46, v46 quad_perm:[1,0,3,2] row_mask:0xf bank_mask:0xf bound_ctrl:1
	v_pk_fma_f32 v[68:69], v[58:59], v[50:51], v[68:69]
	v_pk_fma_f32 v[70:71], v[60:61], v[52:53], v[70:71]
	v_add_f32_dpp v46, v46, v46 quad_perm:[2,3,0,1] row_mask:0xf bank_mask:0xf bound_ctrl:1
	ds_read_b128 v[24:27], v74 offset:28672
	ds_read_b128 v[28:31], v74 offset:28928
	v_add_f32_dpp v46, v46, v46 row_half_mirror row_mask:0xf bank_mask:0xf bound_ctrl:1
	ds_read_b128 v[32:35], v74 offset:29184
	ds_write_b32 v72, v47 offset:9728
	v_add_f32_dpp v46, v46, v46 row_mirror row_mask:0xf bank_mask:0xf bound_ctrl:1
	v_pk_fma_f32 v[58:59], v[54:55], v[46:47], v[68:69] op_sel_hi:[1,0,1]
	v_pk_fma_f32 v[60:61], v[56:57], v[46:47], v[70:71] op_sel_hi:[1,0,1]
	s_waitcnt lgkmcnt(8)
	v_pk_mul_f32 v[0:1], v[58:59], v[0:1] op_sel_hi:[0,1]
	ds_read_b128 v[46:49], v73 offset:29440
	v_pk_fma_f32 v[0:1], v[58:59], v[2:3], v[0:1] op_sel:[1,0,0] op_sel_hi:[1,1,1]
	ds_read_b128 v[76:79], v73 offset:29456
	v_pk_fma_f32 v[0:1], v[60:61], v[16:17], v[0:1] op_sel_hi:[0,1,1]
	ds_read_b32 v44, v75 offset:736
	v_pk_fma_f32 v[0:1], v[60:61], v[18:19], v[0:1] op_sel:[1,0,0] op_sel_hi:[1,1,1]
	v_pk_mul_f32 v[12:13], v[12:13], v[42:43] op_sel_hi:[1,0]
	v_pk_mul_f32 v[14:15], v[14:15], v[42:43] op_sel_hi:[1,0]
	v_add_f32_dpp v0, v0, v0 quad_perm:[1,0,3,2] row_mask:0xf bank_mask:0xf bound_ctrl:1
	v_pk_fma_f32 v[12:13], v[58:59], v[4:5], v[12:13]
	v_pk_fma_f32 v[14:15], v[60:61], v[6:7], v[14:15]
	v_add_f32_dpp v0, v0, v0 quad_perm:[2,3,0,1] row_mask:0xf bank_mask:0xf bound_ctrl:1
	ds_read_b128 v[50:53], v74 offset:29952
	ds_read_b128 v[54:57], v74 offset:30208
	v_add_f32_dpp v0, v0, v0 row_half_mirror row_mask:0xf bank_mask:0xf bound_ctrl:1
	ds_read_b128 v[68:71], v74 offset:30464
	ds_write_b32 v72, v1 offset:10240
	v_add_f32_dpp v0, v0, v0 row_mirror row_mask:0xf bank_mask:0xf bound_ctrl:1
	v_pk_fma_f32 v[58:59], v[8:9], v[0:1], v[12:13] op_sel_hi:[1,0,1]
	v_pk_fma_f32 v[60:61], v[10:11], v[0:1], v[14:15] op_sel_hi:[1,0,1]
	s_waitcnt lgkmcnt(8)
	v_pk_mul_f32 v[20:21], v[58:59], v[20:21] op_sel_hi:[0,1]
	ds_read_b128 v[0:3], v73 offset:30720
	v_pk_fma_f32 v[20:21], v[58:59], v[22:23], v[20:21] op_sel:[1,0,0] op_sel_hi:[1,1,1]
	ds_read_b128 v[16:19], v73 offset:30736
	v_pk_fma_f32 v[20:21], v[60:61], v[36:37], v[20:21] op_sel_hi:[0,1,1]
	ds_read_b32 v42, v75 offset:768
	v_pk_fma_f32 v[20:21], v[60:61], v[38:39], v[20:21] op_sel:[1,0,0] op_sel_hi:[1,1,1]
	v_pk_mul_f32 v[32:33], v[32:33], v[62:63] op_sel_hi:[1,0]
	v_pk_mul_f32 v[34:35], v[34:35], v[62:63] op_sel_hi:[1,0]
	v_add_f32_dpp v20, v20, v20 quad_perm:[1,0,3,2] row_mask:0xf bank_mask:0xf bound_ctrl:1
	v_pk_fma_f32 v[32:33], v[58:59], v[24:25], v[32:33]
	v_pk_fma_f32 v[34:35], v[60:61], v[26:27], v[34:35]
	v_add_f32_dpp v20, v20, v20 quad_perm:[2,3,0,1] row_mask:0xf bank_mask:0xf bound_ctrl:1
	ds_read_b128 v[4:7], v74 offset:31232
	ds_read_b128 v[8:11], v74 offset:31488
	v_add_f32_dpp v20, v20, v20 row_half_mirror row_mask:0xf bank_mask:0xf bound_ctrl:1
	ds_read_b128 v[12:15], v74 offset:31744
	ds_write_b32 v72, v21 offset:10752
	v_add_f32_dpp v20, v20, v20 row_mirror row_mask:0xf bank_mask:0xf bound_ctrl:1
	v_pk_fma_f32 v[58:59], v[28:29], v[20:21], v[32:33] op_sel_hi:[1,0,1]
	v_pk_fma_f32 v[60:61], v[30:31], v[20:21], v[34:35] op_sel_hi:[1,0,1]
	s_waitcnt lgkmcnt(8)
	v_pk_mul_f32 v[46:47], v[58:59], v[46:47] op_sel_hi:[0,1]
	ds_read_b128 v[20:23], v73 offset:32000
	v_pk_fma_f32 v[46:47], v[58:59], v[48:49], v[46:47] op_sel:[1,0,0] op_sel_hi:[1,1,1]
	ds_read_b128 v[36:39], v73 offset:32016
	v_pk_fma_f32 v[46:47], v[60:61], v[76:77], v[46:47] op_sel_hi:[0,1,1]
	ds_read_b32 v62, v75 offset:800
	v_pk_fma_f32 v[46:47], v[60:61], v[78:79], v[46:47] op_sel:[1,0,0] op_sel_hi:[1,1,1]
	v_pk_mul_f32 v[68:69], v[68:69], v[44:45] op_sel_hi:[1,0]
	v_pk_mul_f32 v[70:71], v[70:71], v[44:45] op_sel_hi:[1,0]
	v_add_f32_dpp v46, v46, v46 quad_perm:[1,0,3,2] row_mask:0xf bank_mask:0xf bound_ctrl:1
	v_pk_fma_f32 v[68:69], v[58:59], v[50:51], v[68:69]
	v_pk_fma_f32 v[70:71], v[60:61], v[52:53], v[70:71]
	v_add_f32_dpp v46, v46, v46 quad_perm:[2,3,0,1] row_mask:0xf bank_mask:0xf bound_ctrl:1
	ds_read_b128 v[24:27], v74 offset:32512
	ds_read_b128 v[28:31], v74 offset:32768
	v_add_f32_dpp v46, v46, v46 row_half_mirror row_mask:0xf bank_mask:0xf bound_ctrl:1
	ds_read_b128 v[32:35], v74 offset:33024
	ds_write_b32 v72, v47 offset:11264
	v_add_f32_dpp v46, v46, v46 row_mirror row_mask:0xf bank_mask:0xf bound_ctrl:1
	v_pk_fma_f32 v[58:59], v[54:55], v[46:47], v[68:69] op_sel_hi:[1,0,1]
	v_pk_fma_f32 v[60:61], v[56:57], v[46:47], v[70:71] op_sel_hi:[1,0,1]
	s_waitcnt lgkmcnt(8)
	v_pk_mul_f32 v[0:1], v[58:59], v[0:1] op_sel_hi:[0,1]
	ds_read_b128 v[46:49], v73 offset:33280
	v_pk_fma_f32 v[0:1], v[58:59], v[2:3], v[0:1] op_sel:[1,0,0] op_sel_hi:[1,1,1]
	ds_read_b128 v[76:79], v73 offset:33296
	v_pk_fma_f32 v[0:1], v[60:61], v[16:17], v[0:1] op_sel_hi:[0,1,1]
	ds_read_b32 v44, v75 offset:832
	v_pk_fma_f32 v[0:1], v[60:61], v[18:19], v[0:1] op_sel:[1,0,0] op_sel_hi:[1,1,1]
	v_pk_mul_f32 v[12:13], v[12:13], v[42:43] op_sel_hi:[1,0]
	v_pk_mul_f32 v[14:15], v[14:15], v[42:43] op_sel_hi:[1,0]
	v_add_f32_dpp v0, v0, v0 quad_perm:[1,0,3,2] row_mask:0xf bank_mask:0xf bound_ctrl:1
	v_pk_fma_f32 v[12:13], v[58:59], v[4:5], v[12:13]
	v_pk_fma_f32 v[14:15], v[60:61], v[6:7], v[14:15]
	v_add_f32_dpp v0, v0, v0 quad_perm:[2,3,0,1] row_mask:0xf bank_mask:0xf bound_ctrl:1
	ds_read_b128 v[50:53], v74 offset:33792
	ds_read_b128 v[54:57], v74 offset:34048
	v_add_f32_dpp v0, v0, v0 row_half_mirror row_mask:0xf bank_mask:0xf bound_ctrl:1
	ds_read_b128 v[68:71], v74 offset:34304
	ds_write_b32 v72, v1 offset:11776
	v_add_f32_dpp v0, v0, v0 row_mirror row_mask:0xf bank_mask:0xf bound_ctrl:1
	v_pk_fma_f32 v[58:59], v[8:9], v[0:1], v[12:13] op_sel_hi:[1,0,1]
	v_pk_fma_f32 v[60:61], v[10:11], v[0:1], v[14:15] op_sel_hi:[1,0,1]
	s_waitcnt lgkmcnt(8)
	v_pk_mul_f32 v[20:21], v[58:59], v[20:21] op_sel_hi:[0,1]
	ds_read_b128 v[0:3], v73 offset:34560
	v_pk_fma_f32 v[20:21], v[58:59], v[22:23], v[20:21] op_sel:[1,0,0] op_sel_hi:[1,1,1]
	ds_read_b128 v[16:19], v73 offset:34576
	v_pk_fma_f32 v[20:21], v[60:61], v[36:37], v[20:21] op_sel_hi:[0,1,1]
	ds_read_b32 v42, v75 offset:864
	v_pk_fma_f32 v[20:21], v[60:61], v[38:39], v[20:21] op_sel:[1,0,0] op_sel_hi:[1,1,1]
	v_pk_mul_f32 v[32:33], v[32:33], v[62:63] op_sel_hi:[1,0]
	v_pk_mul_f32 v[34:35], v[34:35], v[62:63] op_sel_hi:[1,0]
	v_add_f32_dpp v20, v20, v20 quad_perm:[1,0,3,2] row_mask:0xf bank_mask:0xf bound_ctrl:1
	v_pk_fma_f32 v[32:33], v[58:59], v[24:25], v[32:33]
	v_pk_fma_f32 v[34:35], v[60:61], v[26:27], v[34:35]
	v_add_f32_dpp v20, v20, v20 quad_perm:[2,3,0,1] row_mask:0xf bank_mask:0xf bound_ctrl:1
	ds_read_b128 v[4:7], v74 offset:35072
	ds_read_b128 v[8:11], v74 offset:35328
	v_add_f32_dpp v20, v20, v20 row_half_mirror row_mask:0xf bank_mask:0xf bound_ctrl:1
	ds_read_b128 v[12:15], v74 offset:35584
	ds_write_b32 v72, v21 offset:12288
	v_add_f32_dpp v20, v20, v20 row_mirror row_mask:0xf bank_mask:0xf bound_ctrl:1
	v_pk_fma_f32 v[58:59], v[28:29], v[20:21], v[32:33] op_sel_hi:[1,0,1]
	v_pk_fma_f32 v[60:61], v[30:31], v[20:21], v[34:35] op_sel_hi:[1,0,1]
	s_waitcnt lgkmcnt(8)
	v_pk_mul_f32 v[46:47], v[58:59], v[46:47] op_sel_hi:[0,1]
	ds_read_b128 v[20:23], v73 offset:35840
	v_pk_fma_f32 v[46:47], v[58:59], v[48:49], v[46:47] op_sel:[1,0,0] op_sel_hi:[1,1,1]
	ds_read_b128 v[36:39], v73 offset:35856
	v_pk_fma_f32 v[46:47], v[60:61], v[76:77], v[46:47] op_sel_hi:[0,1,1]
	ds_read_b32 v62, v75 offset:896
	v_pk_fma_f32 v[46:47], v[60:61], v[78:79], v[46:47] op_sel:[1,0,0] op_sel_hi:[1,1,1]
	v_pk_mul_f32 v[68:69], v[68:69], v[44:45] op_sel_hi:[1,0]
	v_pk_mul_f32 v[70:71], v[70:71], v[44:45] op_sel_hi:[1,0]
	v_add_f32_dpp v46, v46, v46 quad_perm:[1,0,3,2] row_mask:0xf bank_mask:0xf bound_ctrl:1
	v_pk_fma_f32 v[68:69], v[58:59], v[50:51], v[68:69]
	v_pk_fma_f32 v[70:71], v[60:61], v[52:53], v[70:71]
	v_add_f32_dpp v46, v46, v46 quad_perm:[2,3,0,1] row_mask:0xf bank_mask:0xf bound_ctrl:1
	ds_read_b128 v[24:27], v74 offset:36352
	ds_read_b128 v[28:31], v74 offset:36608
	v_add_f32_dpp v46, v46, v46 row_half_mirror row_mask:0xf bank_mask:0xf bound_ctrl:1
	ds_read_b128 v[32:35], v74 offset:36864
	ds_write_b32 v72, v47 offset:12800
	v_add_f32_dpp v46, v46, v46 row_mirror row_mask:0xf bank_mask:0xf bound_ctrl:1
	v_pk_fma_f32 v[58:59], v[54:55], v[46:47], v[68:69] op_sel_hi:[1,0,1]
	v_pk_fma_f32 v[60:61], v[56:57], v[46:47], v[70:71] op_sel_hi:[1,0,1]
	s_waitcnt lgkmcnt(8)
	v_pk_mul_f32 v[0:1], v[58:59], v[0:1] op_sel_hi:[0,1]
	ds_read_b128 v[46:49], v73 offset:37120
	v_pk_fma_f32 v[0:1], v[58:59], v[2:3], v[0:1] op_sel:[1,0,0] op_sel_hi:[1,1,1]
	ds_read_b128 v[76:79], v73 offset:37136
	v_pk_fma_f32 v[0:1], v[60:61], v[16:17], v[0:1] op_sel_hi:[0,1,1]
	ds_read_b32 v44, v75 offset:928
	v_pk_fma_f32 v[0:1], v[60:61], v[18:19], v[0:1] op_sel:[1,0,0] op_sel_hi:[1,1,1]
	v_pk_mul_f32 v[12:13], v[12:13], v[42:43] op_sel_hi:[1,0]
	v_pk_mul_f32 v[14:15], v[14:15], v[42:43] op_sel_hi:[1,0]
	v_add_f32_dpp v0, v0, v0 quad_perm:[1,0,3,2] row_mask:0xf bank_mask:0xf bound_ctrl:1
	v_pk_fma_f32 v[12:13], v[58:59], v[4:5], v[12:13]
	v_pk_fma_f32 v[14:15], v[60:61], v[6:7], v[14:15]
	v_add_f32_dpp v0, v0, v0 quad_perm:[2,3,0,1] row_mask:0xf bank_mask:0xf bound_ctrl:1
	ds_read_b128 v[50:53], v74 offset:37632
	ds_read_b128 v[54:57], v74 offset:37888
	v_add_f32_dpp v0, v0, v0 row_half_mirror row_mask:0xf bank_mask:0xf bound_ctrl:1
	ds_read_b128 v[68:71], v74 offset:38144
	ds_write_b32 v72, v1 offset:13312
	v_add_f32_dpp v0, v0, v0 row_mirror row_mask:0xf bank_mask:0xf bound_ctrl:1
	v_pk_fma_f32 v[58:59], v[8:9], v[0:1], v[12:13] op_sel_hi:[1,0,1]
	v_pk_fma_f32 v[60:61], v[10:11], v[0:1], v[14:15] op_sel_hi:[1,0,1]
	s_waitcnt lgkmcnt(8)
; #define LAS __attribute__((address_space(3)))
; #define RW_LDS_WAIT(X) asm volatile("s_waitcnt lgkmcnt(0)" : "+v"(nk##X), "+v"(dd##X), "+v"(bb##X), "+v"(kp##X), "+v"(rr##X), "+v"(vv##X) :: "memory")
; DI void rwkv_scan_phase(int wv, const Params& P, LAS unsigned char* lds) {
;     ...
;                 f32x2 yacc = (f32x2){0.f, 0.f};
;                 unsigned sbt = sba, vbt = vba; LAS float* ybt = yb;
;                 RW_LDS_LOAD(A, 0); RW_LDS_WAIT(A);
; #pragma unroll 1
;                 for (int tt = 0; tt < RW_T; tt += 16) { sbt = sba + (unsigned)tt * 1280u; vbt = vba + (unsigned)tt * 32u; ybt = yb + tt * 128;
;                     RW_LDS_LOAD(B, 1); RW_STEP(A, 0); RW_LDS_WAIT(B);
;                     RW_LDS_LOAD(A, 2); RW_STEP(B, 1); RW_LDS_WAIT(A);
;                     RW_LDS_LOAD(B, 3); RW_STEP(A, 2); RW_LDS_WAIT(B);
;                     RW_LDS_LOAD(A, 4); RW_STEP(B, 3); RW_LDS_WAIT(A);
;                     RW_LDS_LOAD(B, 5); RW_STEP(A, 4); RW_LDS_WAIT(B);
;                     RW_LDS_LOAD(A, 6); RW_STEP(B, 5); RW_LDS_WAIT(A);
;                     RW_LDS_LOAD(B, 7); RW_STEP(A, 6); RW_LDS_WAIT(B);
;                     RW_LDS_LOAD(A, 8); RW_STEP(B, 7); RW_LDS_WAIT(A);
;                     RW_LDS_LOAD(B, 9); RW_STEP(A, 8); RW_LDS_WAIT(B);
;                     RW_LDS_LOAD(A, 10); RW_STEP(B, 9); RW_LDS_WAIT(A);
;                     RW_LDS_LOAD(B, 11); RW_STEP(A, 10); RW_LDS_WAIT(B);
;                     RW_LDS_LOAD(A, 12); RW_STEP(B, 11); RW_LDS_WAIT(A);
;                     RW_LDS_LOAD(B, 13); RW_STEP(A, 12); RW_LDS_WAIT(B);
;                     RW_LDS_LOAD(A, 14); RW_STEP(B, 13); RW_LDS_WAIT(A);
;                     RW_LDS_LOAD(B, 15); RW_STEP(A, 14); RW_LDS_WAIT(B);
;                     RW_LDS_LOAD(A, 16); RW_STEP(B, 15); RW_LDS_WAIT(A);
;                 }
;                 yb[(RW_T - 1) * 128] = yacc[0] + yacc[1];
	v_pk_mul_f32 v[20:21], v[58:59], v[20:21] op_sel_hi:[0,1]
	ds_read_b128 v[0:3], v73 offset:38400
	v_pk_fma_f32 v[20:21], v[58:59], v[22:23], v[20:21] op_sel:[1,0,0] op_sel_hi:[1,1,1]
	ds_read_b128 v[16:19], v73 offset:38416
	v_pk_fma_f32 v[20:21], v[60:61], v[36:37], v[20:21] op_sel_hi:[0,1,1]
	ds_read_b32 v42, v75 offset:960
	v_pk_fma_f32 v[20:21], v[60:61], v[38:39], v[20:21] op_sel:[1,0,0] op_sel_hi:[1,1,1]
	v_pk_mul_f32 v[32:33], v[32:33], v[62:63] op_sel_hi:[1,0]
	v_pk_mul_f32 v[34:35], v[34:35], v[62:63] op_sel_hi:[1,0]
	v_add_f32_dpp v20, v20, v20 quad_perm:[1,0,3,2] row_mask:0xf bank_mask:0xf bound_ctrl:1
	v_pk_fma_f32 v[32:33], v[58:59], v[24:25], v[32:33]
	v_pk_fma_f32 v[34:35], v[60:61], v[26:27], v[34:35]
	v_add_f32_dpp v20, v20, v20 quad_perm:[2,3,0,1] row_mask:0xf bank_mask:0xf bound_ctrl:1
	ds_read_b128 v[4:7], v74 offset:38912
	ds_read_b128 v[8:11], v74 offset:39168
	v_add_f32_dpp v20, v20, v20 row_half_mirror row_mask:0xf bank_mask:0xf bound_ctrl:1
	ds_read_b128 v[12:15], v74 offset:39424
	ds_write_b32 v72, v21 offset:13824
	v_add_f32_dpp v20, v20, v20 row_mirror row_mask:0xf bank_mask:0xf bound_ctrl:1
	v_pk_fma_f32 v[58:59], v[28:29], v[20:21], v[32:33] op_sel_hi:[1,0,1]
	v_pk_fma_f32 v[60:61], v[30:31], v[20:21], v[34:35] op_sel_hi:[1,0,1]
	s_waitcnt lgkmcnt(8)
	v_pk_mul_f32 v[46:47], v[58:59], v[46:47] op_sel_hi:[0,1]
	ds_read_b128 v[20:23], v73 offset:39680
	v_pk_fma_f32 v[46:47], v[58:59], v[48:49], v[46:47] op_sel:[1,0,0] op_sel_hi:[1,1,1]
	ds_read_b128 v[36:39], v73 offset:39696
	v_pk_fma_f32 v[46:47], v[60:61], v[76:77], v[46:47] op_sel_hi:[0,1,1]
	ds_read_b32 v62, v75 offset:992
	v_pk_fma_f32 v[46:47], v[60:61], v[78:79], v[46:47] op_sel:[1,0,0] op_sel_hi:[1,1,1]
	v_pk_mul_f32 v[68:69], v[68:69], v[44:45] op_sel_hi:[1,0]
	v_pk_mul_f32 v[70:71], v[70:71], v[44:45] op_sel_hi:[1,0]
	v_add_f32_dpp v46, v46, v46 quad_perm:[1,0,3,2] row_mask:0xf bank_mask:0xf bound_ctrl:1
	v_pk_fma_f32 v[68:69], v[58:59], v[50:51], v[68:69]
	v_pk_fma_f32 v[70:71], v[60:61], v[52:53], v[70:71]
	v_add_f32_dpp v46, v46, v46 quad_perm:[2,3,0,1] row_mask:0xf bank_mask:0xf bound_ctrl:1
	ds_read_b128 v[24:27], v74 offset:40192
	ds_read_b128 v[28:31], v74 offset:40448
	v_add_f32_dpp v46, v46, v46 row_half_mirror row_mask:0xf bank_mask:0xf bound_ctrl:1
	ds_read_b128 v[32:35], v74 offset:40704
	ds_write_b32 v72, v47 offset:14336
	v_add_f32_dpp v46, v46, v46 row_mirror row_mask:0xf bank_mask:0xf bound_ctrl:1
	v_pk_fma_f32 v[58:59], v[54:55], v[46:47], v[68:69] op_sel_hi:[1,0,1]
	v_pk_fma_f32 v[60:61], v[56:57], v[46:47], v[70:71] op_sel_hi:[1,0,1]
	s_waitcnt lgkmcnt(8)
	v_pk_mul_f32 v[0:1], v[58:59], v[0:1] op_sel_hi:[0,1]
	v_pk_mul_f32 v[12:13], v[12:13], v[42:43] op_sel_hi:[1,0]
	v_pk_fma_f32 v[0:1], v[58:59], v[2:3], v[0:1] op_sel:[1,0,0] op_sel_hi:[1,1,1]
	v_pk_mul_f32 v[14:15], v[14:15], v[42:43] op_sel_hi:[1,0]
	v_pk_fma_f32 v[0:1], v[60:61], v[16:17], v[0:1] op_sel_hi:[0,1,1]
	v_pk_fma_f32 v[12:13], v[58:59], v[4:5], v[12:13]
	v_pk_fma_f32 v[0:1], v[60:61], v[18:19], v[0:1] op_sel:[1,0,0] op_sel_hi:[1,1,1]
	v_pk_fma_f32 v[14:15], v[60:61], v[6:7], v[14:15]
	ds_write_b32 v72, v1 offset:14848
	v_add_f32_dpp v0, v0, v0 quad_perm:[1,0,3,2] row_mask:0xf bank_mask:0xf bound_ctrl:1
	ds_read_b128 v[46:49], v40
	s_add_i32 s47, s47, 1
	v_add_f32_dpp v0, v0, v0 quad_perm:[2,3,0,1] row_mask:0xf bank_mask:0xf bound_ctrl:1
	s_add_i32 s42, s42, 0x4000
	s_cmp_eq_u32 s42, 0xc000
	v_add_f32_dpp v0, v0, v0 row_half_mirror row_mask:0xf bank_mask:0xf bound_ctrl:1
	s_cselect_b32 s42, 0, s42
	s_lshl_b32 s40, s47, 5
	v_add_f32_dpp v0, v0, v0 row_mirror row_mask:0xf bank_mask:0xf bound_ctrl:1
	v_pk_fma_f32 v[58:59], v[8:9], v[0:1], v[12:13] op_sel_hi:[1,0,1]
	v_pk_fma_f32 v[60:61], v[10:11], v[0:1], v[14:15] op_sel_hi:[1,0,1]
	s_waitcnt lgkmcnt(0)
	s_barrier
	v_pk_mul_f32 v[20:21], v[58:59], v[20:21] op_sel_hi:[0,1]
	v_pk_mul_f32 v[32:33], v[32:33], v[62:63] op_sel_hi:[1,0]
	v_pk_fma_f32 v[20:21], v[58:59], v[22:23], v[20:21] op_sel:[1,0,0] op_sel_hi:[1,1,1]
	v_pk_mul_f32 v[34:35], v[34:35], v[62:63] op_sel_hi:[1,0]
	v_pk_fma_f32 v[20:21], v[60:61], v[36:37], v[20:21] op_sel_hi:[0,1,1]
	v_pk_fma_f32 v[32:33], v[58:59], v[24:25], v[32:33]
	v_pk_fma_f32 v[20:21], v[60:61], v[38:39], v[20:21] op_sel:[1,0,0] op_sel_hi:[1,1,1]
	v_pk_fma_f32 v[34:35], v[60:61], v[26:27], v[34:35]
	ds_write_b32 v72, v21 offset:15360
	v_add_f32_dpp v20, v20, v20 quad_perm:[1,0,3,2] row_mask:0xf bank_mask:0xf bound_ctrl:1
	s_and_b32 s40, s40, 32
	s_mul_i32 s41, s40, 0x500
	v_add_f32_dpp v20, v20, v20 quad_perm:[2,3,0,1] row_mask:0xf bank_mask:0xf bound_ctrl:1
	v_add_u32_e32 v74, s41, v45
	v_add_u32_e32 v73, v74, v45
	v_add_f32_dpp v20, v20, v20 row_half_mirror row_mask:0xf bank_mask:0xf bound_ctrl:1
	v_lshl_add_u32 v75, s40, 5, v63
	v_add_u32_e32 v67, s42, v66
	v_add_f32_dpp v20, v20, v20 row_mirror row_mask:0xf bank_mask:0xf bound_ctrl:1
	v_pk_fma_f32 v[58:59], v[28:29], v[20:21], v[32:33] op_sel_hi:[1,0,1]
	v_pk_fma_f32 v[60:61], v[30:31], v[20:21], v[34:35] op_sel_hi:[1,0,1]
	s_lshl_b32 s41, s40, 3
	s_add_i32 s41, s41, 0x20800
	v_add_u32_e32 v40, s41, v45
	v_pk_mul_f32 v[64:65], v[46:47], v[58:59]
	ds_read_b128 v[0:3], v73
	v_pk_fma_f32 v[64:65], v[48:49], v[60:61], v[64:65]
	ds_read_b128 v[16:19], v73 offset:16
	s_cmpk_eq_i32 s47, 0x100
	v_add_f32_e32 v64, v64, v65
	ds_read_b32 v42, v75
	ds_write_b32 v72, v64 offset:15872
	v_mov_b32_e32 v72, v67
	ds_read_b128 v[4:7], v74 offset:512
	ds_read_b128 v[8:11], v74 offset:768
	ds_read_b128 v[12:15], v74 offset:1024
	ds_read_b128 v[20:23], v73 offset:1280
	ds_read_b128 v[36:39], v73 offset:1296
	ds_read_b32 v62, v75 offset:32
	ds_read_b128 v[24:27], v74 offset:1792
	ds_read_b128 v[28:31], v74 offset:2048
	ds_read_b128 v[32:35], v74 offset:2304
	s_cbranch_scc0 .Lscan_chunk
	s_waitcnt lgkmcnt(0)
	s_barrier

; DI void rwkv_scan_phase(int wv, const Params& P, LAS unsigned char* lds) {
;     ...
;             const int ch = h * 64 + lane;
;             const float kkw = P.in[35][ch], kaw = P.in[36][ch], rkw = P.in[37][ch];
;             const int hf = lane >> 5, c2 = lane & 31, chp = h * 64 + 2 * c2;
;             const f32x2 kkw2 = *(const f32x2*)(P.in[35] + chp), kaw2 = *(const f32x2*)(P.in[36] + chp), rkw2 = *(const f32x2*)(P.in[37] + chp);
;             unsigned gk[3], ga[3], gr[3], gl[3]; float gv[3];
;     ...
;             RW_LOADG(0)
; #pragma unroll 1
;             for (int ck = -1; ck <= nck; ++ck) {
;                 {
;                     if (ck >= 1) { const LAS float* yb = ybuf + ((ck - 1) & 1) * RW_T * 128;
; #pragma unroll 2
;                         for (int it = pw; it < 64; it += 6) { const float y = row16_sum(yb[it * 64 + lane]);
;                             const float y0 = __builtin_bit_cast(float, __builtin_amdgcn_readlane(__builtin_bit_cast(int, y), 0)), y1 = __builtin_bit_cast(float, __builtin_amdgcn_readlane(__builtin_bit_cast(int, y), 16)),
;                                         y2 = __builtin_bit_cast(float, __builtin_amdgcn_readlane(__builtin_bit_cast(int, y), 32)), y3 = __builtin_bit_cast(float, __builtin_amdgcn_readlane(__builtin_bit_cast(int, y), 48));
;                             if (lane == 0) { u32x2 w; w.x = pk2(y0, y1); w.y = pk2(y2, y3); *(u32x2*)(YS + ((size_t)b * SEQ + (ck - 1) * RW_T + (it >> 1)) * 1024 + h * 64 + rg * 8 + (it & 1) * 4) = w; } } }
;                     if (ck + 1 < nck) { const int cn = ck + 1, buf = cn & 1;
; #pragma unroll
;                         for (int i = 0; i < 3; ++i) { const int pp = pw + 6 * i; if (pp < 16) { const int tt = 2 * pp + hf; const size_t row = (size_t)b * SEQ + cn * RW_T + tt;
;                             const f32x2 k = {bflo(gk[i]), bfhi(gk[i])}, a = {bflo(ga[i]), bfhi(ga[i])}, r = {bflo(gr[i]), bfhi(gr[i])};
;                             const h16x2 lh = __builtin_bit_cast(h16x2, gl[i]);
;                             const f32x2 kr = k * kkw2, kp = k * ((a - 1.f) * kaw2 + 1.f);
;                             const float sp = kr[0] * kr[0] + kr[1] * kr[1], rp = r[0] * kp[0] * rkw2[0] + r[1] * kp[1] * rkw2[1];
;                             const bool odd = lane & 1;
;                             float red = (odd ? rp : sp) + dpp_f<0xB1>(odd ? sp : rp);
.LBB0_3185:
	s_andn2_saveexec_b64 s[40:41], s[20:21]
	s_cbranch_execz .LBB0_3174
	v_readfirstlane_b32 s55, v41
	s_mov_b32 s68, s55
	s_and_b32 s66, s55, 2
	s_cmp_lg_u32 s66, 0
	s_cbranch_scc1 .Lprod_idle
	s_lshr_b32 s66, s55, 1
	s_and_b32 s55, s55, 1
	s_or_b32 s55, s55, s66
	s_and_b32 s67, s46, 7
	s_bfe_u32 s59, s46, 0x40003
	s_lshr_b32 s60, s46, 7
	s_lshl_b32 s60, s60, 13
	s_lshl_b32 s66, s55, 3
	s_add_i32 s60, s60, s66
	v_mbcnt_lo_u32_b32 v0, -1, 0
	v_mbcnt_hi_u32_b32 v0, -1, v0
	v_and_b32_e32 v1, 31, v0
	v_lshrrev_b32_e32 v31, 5, v0
	s_lshl_b32 s61, s59, 6
	v_lshl_add_u32 v32, v1, 1, s61
	v_lshlrev_b32_e32 v33, 2, v32
	global_load_dwordx2 v[4:5], v33, s[24:25]
	global_load_dwordx2 v[6:7], v33, s[26:27]
	global_load_dwordx2 v[8:9], v33, s[38:39]
	v_add_u32_e32 v34, s60, v31
	v_lshlrev_b32_e32 v35, 11, v34
	v_lshl_add_u32 v12, v32, 1, v35
	v_add_u32_e32 v13, 0x1000, v12
	v_add_u32_e32 v14, 0x2000, v12
	v_add_u32_e32 v15, 0x3000, v12
	v_and_b32_e32 v36, 7, v0
	s_lshl_b32 s66, s67, 3
	s_add_i32 s66, s66, s61
	v_add_u32_e32 v37, s66, v36
	v_lshl_add_u32 v16, v37, 1, v35
	v_add_u32_e32 v17, 0x1000, v16
	v_add_u32_e32 v18, 0x2000, v16
	v_add_u32_e32 v19, 0x3000, v16
	s_lshl_b32 s66, s55, 3
	v_add_u32_e32 v37, s66, v31
	v_mul_u32_u24_e32 v2, 0x500, v37
	v_lshl_add_u32 v2, v1, 3, v2
	v_lshlrev_b32_e32 v3, 5, v37
	v_lshl_add_u32 v3, v1, 2, v3
	v_add_u32_e32 v3, 0x14000, v3
	s_lshl_b32 s66, s59, 2
	v_lshl_add_u32 v10, v34, 6, s66
	v_lshrrev_b32_e32 v37, 3, v0
	s_lshl_b32 s66, s55, 3
	v_add_u32_e32 v37, s66, v37
	v_lshlrev_b32_e32 v11, 9, v37
	v_lshl_add_u32 v11, v36, 6, v11
	v_add_u32_e32 v11, 0x14800, v11
	s_lshr_b32 s66, s46, 7
	s_lshl_b32 s66, s66, 13
	v_add_u32_e32 v37, s66, v37
	v_lshlrev_b32_e32 v37, 11, v37
	s_lshl_b32 s66, s67, 3
	s_add_i32 s66, s66, s61
	v_add_u32_e32 v38, s66, v36
	v_lshl_add_u32 v20, v38, 1, v37
	v_or_b32_e32 v38, s67, v1
	v_cmp_eq_u32_e64 s[42:43], 0, v38
	s_mov_b32 s57, -1
	s_mov_b32 s69, 0
	s_mov_b32 s67, 0
	s_add_u32 s60, s28, s67
	s_addc_u32 s61, s29, 0
	global_load_dword v44, v12, s[60:61]
	global_load_dword v49, v13, s[60:61]
	global_load_dword v54, v14, s[60:61]
	global_load_dword v59, v15, s[60:61]
	s_add_u32 s60, s34, s67
	s_addc_u32 s61, s35, 0
	global_load_dword v45, v12, s[60:61]
	global_load_dword v50, v13, s[60:61]
	global_load_dword v55, v14, s[60:61]
	global_load_dword v60, v15, s[60:61]
	s_add_u32 s60, s22, s67
	s_addc_u32 s61, s23, 0
	global_load_dword v46, v12, s[60:61]
	global_load_dword v51, v13, s[60:61]
	global_load_dword v56, v14, s[60:61]
	global_load_dword v61, v15, s[60:61]
	s_add_u32 s60, s36, s67
	s_addc_u32 s61, s37, 0
	global_load_dword v47, v12, s[60:61]
	global_load_dword v52, v13, s[60:61]
	global_load_dword v57, v14, s[60:61]
	global_load_dword v62, v15, s[60:61]
	s_add_u32 s60, s30, s67
	s_addc_u32 s61, s31, 0
	global_load_ushort v48, v16, s[60:61]
	global_load_ushort v53, v17, s[60:61]
	global_load_ushort v58, v18, s[60:61]
	global_load_ushort v63, v19, s[60:61]
	s_add_u32 s60, s22, s67
	s_addc_u32 s61, s23, 0
	s_sub_u32 s60, s60, 0x800
	s_subb_u32 s61, s61, 0
	global_load_dword v0, v12, s[60:61]
	global_load_dword v40, v13, s[60:61]
	global_load_dword v43, v14, s[60:61]
	global_load_dword v41, v15, s[60:61]
.Lprod_loop:
	s_cmp_lt_i32 s57, 2
	s_cbranch_scc1 .Lprod_stage
	v_add_u32_e32 v21, s69, v11
	s_add_i32 s69, s69, 0x4000
	s_cmp_eq_u32 s69, 0xc000
	s_cselect_b32 s69, 0, s69
	ds_read_b128 v[24:27], v21
	ds_read_b128 v[28:31], v21 offset:16
	ds_read_b128 v[32:35], v21 offset:32
	ds_read_b128 v[36:39], v21 offset:48
.Lprod_stage:
	s_cmp_gt_i32 s57, 0xfe
	s_cbranch_scc1 .Lprod_flush
	s_add_i32 s67, s57, 1
	s_and_b32 s59, s67, 1
	s_mul_i32 s60, s59, 0xa000
	v_add_u32_e32 v22, s60, v2
	s_lshl_b32 s60, s59, 10
	v_add_u32_e32 v23, s60, v3
	v_lshl_add_u32 v21, v1, 3, v22
	s_lshl_b32 s66, s59, 8
	s_add_i32 s66, s66, 0x20800
	s_lshl_b32 s60, s67, 11
	s_add_u32 s62, s50, s60
	s_addc_u32 s63, s51, 0
	s_waitcnt vmcnt(0)
	v_lshlrev_b32_e32 v64, 16, v45
	v_and_b32_e32 v65, 0xffff0000, v45
	v_pk_add_f32 v[72:73], v[64:65], -1.0 op_sel_hi:[1,0]
	v_lshlrev_b32_e32 v66, 16, v44
	v_and_b32_e32 v67, 0xffff0000, v44
	v_pk_fma_f32 v[72:73], v[6:7], v[72:73], 1.0 op_sel_hi:[1,1,0]
	v_and_b32_e32 v69, 0xffff0000, v46
	v_pk_mul_f32 v[70:71], v[4:5], v[66:67]
	v_pk_mul_f32 v[66:67], v[72:73], v[66:67]
	v_lshlrev_b32_e32 v68, 16, v46
	v_mul_f32_e32 v75, v67, v69
	v_pk_mul_f32 v[72:73], v[70:71], v[70:71]
	v_mul_f32_e32 v74, v66, v68
	v_mul_f32_e32 v75, v9, v75
	v_add_f32_e32 v76, v72, v73
	v_fmac_f32_e32 v75, v8, v74
	v_cndmask_b32_e64 v74, v75, v76, s[8:9]
	v_cndmask_b32_e64 v76, v76, v75, s[8:9]
	v_cvt_f32_f16_e32 v77, v47
	v_cvt_f32_f16_sdwa v78, v47 dst_sel:DWORD dst_unused:UNUSED_PAD src0_sel:WORD_1
	v_add_f32_dpp v76, v76, v74 quad_perm:[1,0,3,2] row_mask:0xf bank_mask:0xf bound_ctrl:1
	v_mul_f32_e32 v77, 0x3fb8aa3b, v77
	s_nop 0
	v_add_f32_dpp v76, v76, v76 quad_perm:[2,3,0,1] row_mask:0xf bank_mask:0xf bound_ctrl:1
	v_exp_f32_e32 v72, v77
	v_mul_f32_e32 v77, 0x3fb8aa3b, v78
	v_add_f32_dpp v76, v76, v76 row_ror:4 row_mask:0xf bank_mask:0xf bound_ctrl:1
	v_exp_f32_e32 v73, v77
	s_nop 0
	v_add_f32_dpp v76, v76, v76 row_ror:8 row_mask:0xf bank_mask:0xf bound_ctrl:1
	v_mov_b32_e32 v74, v76
	s_nop 1
	v_permlane16_swap_b32_e32 v76, v74
	v_add_f32_e32 v76, v76, v74
	s_nop 1
	v_mov_b32_dpp v74, v76 quad_perm:[1,0,3,2] row_mask:0xf bank_mask:0xf bound_ctrl:1
	v_cndmask_b32_e64 v75, v74, v76, s[8:9]
	v_max_f32_e32 v75, v75, v75
	v_max_f32_e32 v75, 0x179abe15, v75
	v_rsq_f32_e32 v42, v75
	v_cndmask_b32_e64 v76, v76, v74, s[8:9]
	v_lshlrev_b32_e32 v79, 16, v48
	v_pk_mul_f32 v[70:71], v[70:71], v[42:43] op_sel_hi:[1,0] neg_lo:[0,1] neg_hi:[0,1]
	ds_write_b64 v22, v[72:73] offset:512
	v_pk_mul_f32 v[64:65], v[70:71], v[64:65] neg_lo:[1,0] neg_hi:[1,0]
	ds_write_b64 v22, v[66:67] offset:1024
	v_lshl_add_u32 v77, v1, 3, s66
	ds_write_b64 v22, v[64:65] offset:768
	v_mov_b32_e32 v72, v71
	v_lshlrev_b32_e32 v71, 16, v0
	v_and_b32_e32 v73, 0xffff0000, v0
	ds_write_b128 v21, v[70:73]
	s_and_saveexec_b64 s[60:61], s[42:43]
	s_cbranch_execz .Lprod_rk_skip_0
	global_store_dword v10, v76, s[62:63]

; #define LAS __attribute__((address_space(3)))
; DI void rwkv_scan_phase(int wv, const Params& P, LAS unsigned char* lds) {
;     ...
;                     if (ck >= 1) { const LAS float* yb = ybuf + ((ck - 1) & 1) * RW_T * 128;
; #pragma unroll 2
;                         for (int it = pw; it < 64; it += 6) { const float y = row16_sum(yb[it * 64 + lane]);
;                             const float y0 = __builtin_bit_cast(float, __builtin_amdgcn_readlane(__builtin_bit_cast(int, y), 0)), y1 = __builtin_bit_cast(float, __builtin_amdgcn_readlane(__builtin_bit_cast(int, y), 16)),
;                                         y2 = __builtin_bit_cast(float, __builtin_amdgcn_readlane(__builtin_bit_cast(int, y), 32)), y3 = __builtin_bit_cast(float, __builtin_amdgcn_readlane(__builtin_bit_cast(int, y), 48));
;                             if (lane == 0) { u32x2 w; w.x = pk2(y0, y1); w.y = pk2(y2, y3); *(u32x2*)(YS + ((size_t)b * SEQ + (ck - 1) * RW_T + (it >> 1)) * 1024 + h * 64 + rg * 8 + (it & 1) * 4) = w; } } }
;                     if (ck + 1 < nck) { const int cn = ck + 1, buf = cn & 1;
; #pragma unroll
;                         for (int i = 0; i < 3; ++i) { const int pp = pw + 6 * i; if (pp < 16) { const int tt = 2 * pp + hf; const size_t row = (size_t)b * SEQ + cn * RW_T + tt;
;                             const f32x2 k = {bflo(gk[i]), bfhi(gk[i])}, a = {bflo(ga[i]), bfhi(ga[i])}, r = {bflo(gr[i]), bfhi(gr[i])};
;                             const h16x2 lh = __builtin_bit_cast(h16x2, gl[i]);
;                             const f32x2 kr = k * kkw2, kp = k * ((a - 1.f) * kaw2 + 1.f);
;                             const float sp = kr[0] * kr[0] + kr[1] * kr[1], rp = r[0] * kp[0] * rkw2[0] + r[1] * kp[1] * rkw2[1];
;                             const bool odd = lane & 1;
;                             float red = (odd ? rp : sp) + dpp_f<0xB1>(odd ? sp : rp);
;                             red += dpp_f<0x4E>(red); red += dpp_f<0x124>(red); red += dpp_f<0x128>(red);
;                             { auto x = __builtin_amdgcn_permlane16_swap(__float_as_uint(red), __float_as_uint(red), false, false); red = __uint_as_float(x[0]) + __uint_as_float(x[1]); }
;                             const float oth = dpp_f<0xB1>(red); const float ss = odd ? oth : red, rks = odd ? red : oth;
;                             const f32x2 kk = kr * __builtin_amdgcn_rsqf(fmaxf(ss, 1e-24f));
.Lprod_flush:
	s_cmp_lt_i32 s57, 2
	s_cbranch_scc1 .Lprod_sync
	s_waitcnt lgkmcnt(0)
	v_pk_add_f32 v[24:25], v[24:25], v[26:27]
	v_pk_add_f32 v[28:29], v[28:29], v[30:31]
	v_pk_add_f32 v[32:33], v[32:33], v[34:35]
	v_pk_add_f32 v[36:37], v[36:37], v[38:39]
	v_pk_add_f32 v[24:25], v[24:25], v[28:29]
	v_pk_add_f32 v[32:33], v[32:33], v[36:37]
	s_add_i32 s67, s57, -2
	s_lshl_b32 s67, s67, 16
	v_pk_add_f32 v[24:25], v[24:25], v[32:33]
	s_add_u32 s60, s44, s67
	s_addc_u32 s61, s45, 0
	v_add_f32_e32 v24, v24, v25
	s_nop 1
	v_mov_b32_dpp v25, v24 quad_perm:[1,0,3,2] row_mask:0xf bank_mask:0xf bound_ctrl:1
	s_nop 0
	v_cvt_pk_bf16_f32 v24, v24, v25
	s_mov_b64 exec, s[8:9]
	global_store_dword v20, v24, s[60:61]
	s_mov_b64 exec, -1
.Lprod_sync:
	s_cmpk_eq_i32 s57, 0x101
	s_cbranch_scc1 .Lprod_exit
	s_waitcnt lgkmcnt(0)
	s_barrier
	s_add_i32 s57, s57, 1
	s_branch .Lprod_loop

; DI void rwkv_scan_phase(int wv, const Params& P, LAS unsigned char* lds) {
;     ...
;                 if (ck < nck) __syncthreads();
.Lprod_idle:
	s_movk_i32 s57, 0x102
